# layer boundary barrier: waiters invalidate L1 on arrival (hidden in the wait) instead of after release; waiters poll global generation word
# speedup vs baseline: 1.0103x; 1.0103x over previous
.LBB0_1052:
	s_or_b64 exec, exec, s[8:9]
	v_cvt_f32_u32_e32 v4, v2
	s_waitcnt vmcnt(0)
	v_readfirstlane_b32 s2, v3
	v_sub_u32_e32 v3, 0, v2
	v_rcp_iflag_f32_e32 v4, v4
	v_add_u32_e32 v5, s2, v1
	v_mul_f32_e32 v4, 0x4f7ffffe, v4
	v_cvt_u32_f32_e32 v4, v4
	v_mul_lo_u32 v1, v3, v4
	v_mul_hi_u32 v1, v4, v1
	v_add_u32_e32 v1, v4, v1
	v_mul_hi_u32 v1, v5, v1
	v_mul_lo_u32 v3, v1, v2
	v_sub_u32_e32 v3, v5, v3
	v_add_u32_e32 v4, 1, v1
	v_cmp_ge_u32_e32 vcc, v3, v2
	s_nop 1
	v_cndmask_b32_e32 v1, v1, v4, vcc
	v_sub_u32_e32 v4, v3, v2
	v_cndmask_b32_e32 v3, v3, v4, vcc
	v_add_u32_e32 v4, 1, v1
	v_cmp_ge_u32_e32 vcc, v3, v2
	v_add_u32_e32 v3, 1, v5
	s_nop 0
	v_cndmask_b32_e32 v1, v1, v4, vcc
	v_mul_lo_u32 v4, v2, v1
	v_add_u32_e32 v2, v4, v2
	v_cmp_ne_u32_e32 vcc, v3, v2
	s_and_saveexec_b64 s[2:3], vcc
	s_xor_b64 s[2:3], exec, s[2:3]
	s_cbranch_execz .LBB0_1066
	buffer_inv sc1
	s_mov_b64 s[10:11], 0x3e38aa3b
	s_movk_i32 s8, 0xd40
	s_mov_b32 s9, s11
	s_lshl_b64 s[8:9], s[8:9], 2
	v_readlane_b32 s10, v252, 0
	v_readlane_b32 s11, v252, 1
	s_add_u32 s10, s10, s8
	s_addc_u32 s11, s11, s9
	s_nop 2
	global_load_dword v0, v193, s[10:11] sc1
	s_waitcnt vmcnt(0)
	v_cmp_eq_u32_e32 vcc, v0, v1
	s_and_saveexec_b64 s[8:9], vcc
	s_cbranch_execz .LBB0_1065
	s_mov_b32 s23, 1
	s_mov_b64 s[12:13], 0
	s_branch .LBB0_1056
